# final rmsnorm row loop software-pipelined: gains loaded once, next row prefetched before stores
# speedup vs baseline: 1.0376x; 1.0052x over previous
; DI void final_norm_rows(const Prm& p, int gw, int ngw, int lane) {
;     for (int r = gw; r < ROW_META; r += ngw) {
;         float* x = p.out + (size_t)r * D; f32x4 v[4]; float ss = 0.f;
; #pragma unroll
;         for (int j = 0; j < 4; ++j) { v[j] = ((const f32x4*)x)[lane + 64 * j]; ss += v[j].x * v[j].x + v[j].y * v[j].y + v[j].z * v[j].z + v[j].w * v[j].w; }
;         ss = wave_sum(ss); const float rstd = rsqrtf(ss * (1.f / D) + 1e-6f);
; #pragma unroll
;         for (int j = 0; j < 4; ++j) { const f32x4 g = ((const f32x4*)p.final_norm)[lane + 64 * j]; ((f32x4*)x)[lane + 64 * j] = (f32x4){v[j].x * rstd * g.x, v[j].y * rstd * g.y, v[j].z * rstd * g.z, v[j].w * rstd * g.w}; }
;     }
.LBB0_2630:
	s_or_b64 exec, exec, s[0:1]
	s_waitcnt lgkmcnt(0)
	s_barrier
	v_readlane_b32 s1, v247, 43
	v_readfirstlane_b32 s0, v212
	s_ashr_i32 s0, s0, 6
	s_add_i32 s0, s0, s1
	s_cmp_gt_i32 s0, 0x87ff
	s_cbranch_scc1 .LBB0_2633
	s_ashr_i32 s1, s0, 31
	s_lshl_b64 s[2:3], s[0:1], 12
	v_and_b32_e32 v0, 63, v212
	s_add_u32 s2, s30, s2
	v_lshlrev_b32_e32 v2, 4, v0
	v_mov_b32_e32 v3, 0
	s_addc_u32 s3, s31, s3
	v_lshl_add_u64 v[0:1], s[28:29], 0, v[2:3]
	v_lshl_add_u64 v[2:3], s[2:3], 0, v[2:3]
	s_mov_b64 s[2:3], 0xc00
	s_ashr_i32 s71, s70, 31
	v_lshl_add_u64 v[2:3], v[2:3], 0, s[2:3]
	s_lshl_b64 s[2:3], s[70:71], 12
	v_mov_b32_e32 v4, 0x358637bd
	s_mov_b32 s1, 0x800000
	global_load_dwordx4 v[116:119], v[0:1], off
	global_load_dwordx4 v[120:123], v[0:1], off offset:1024
	global_load_dwordx4 v[124:127], v[0:1], off offset:2048
	global_load_dwordx4 v[128:131], v[0:1], off offset:3072
	global_load_dwordx4 v[140:143], v[2:3], off offset:-3072
	global_load_dwordx4 v[144:147], v[2:3], off offset:-2048
	global_load_dwordx4 v[148:151], v[2:3], off offset:-1024
	global_load_dwordx4 v[152:155], v[2:3], off
	s_waitcnt vmcnt(0)
.LBB0_2632:
	s_add_i32 s0, s0, s70
	s_cmp_lt_i32 s0, 0x8800
	s_waitcnt vmcnt(4)
	v_mov_b64_e32 v[100:101], v[140:141]
	v_mov_b64_e32 v[102:103], v[142:143]
	v_mov_b64_e32 v[104:105], v[144:145]
	v_mov_b64_e32 v[106:107], v[146:147]
	v_mov_b64_e32 v[108:109], v[148:149]
	v_mov_b64_e32 v[110:111], v[150:151]
	v_mov_b64_e32 v[112:113], v[152:153]
	v_mov_b64_e32 v[114:115], v[154:155]
	s_cbranch_scc0 .Lfn_nopf
	v_lshl_add_u64 v[156:157], v[2:3], 0, s[2:3]
	global_load_dwordx4 v[140:143], v[156:157], off offset:-3072
	global_load_dwordx4 v[144:147], v[156:157], off offset:-2048
	global_load_dwordx4 v[148:151], v[156:157], off offset:-1024
	global_load_dwordx4 v[152:155], v[156:157], off
.Lfn_nopf:
	v_mov_b32_e32 v28, v101
	v_mov_b32_e32 v29, v105
	v_mov_b32_e32 v26, v100
	v_mov_b32_e32 v27, v104
	v_mov_b32_e32 v36, v109
	v_mov_b32_e32 v37, v113
	v_pk_mul_f32 v[28:29], v[28:29], v[28:29]
	v_mov_b32_e32 v30, v102
	v_mov_b32_e32 v31, v106
	v_mov_b32_e32 v34, v108
	v_mov_b32_e32 v35, v112
	v_pk_mul_f32 v[36:37], v[36:37], v[36:37]
	v_pk_fma_f32 v[26:27], v[26:27], v[26:27], v[28:29]
	v_mov_b32_e32 v32, v103
	v_mov_b32_e32 v33, v107
	v_mov_b32_e32 v38, v110
	v_mov_b32_e32 v39, v114
	v_pk_fma_f32 v[28:29], v[34:35], v[34:35], v[36:37]
	v_pk_fma_f32 v[26:27], v[30:31], v[30:31], v[26:27]
	v_mov_b32_e32 v40, v111
	v_mov_b32_e32 v41, v115
	v_pk_fma_f32 v[28:29], v[38:39], v[38:39], v[28:29]
	v_pk_fma_f32 v[26:27], v[32:33], v[32:33], v[26:27]
	v_pk_fma_f32 v[28:29], v[40:41], v[40:41], v[28:29]
	v_add_f32_e32 v5, v26, v27
	v_add_f32_e32 v5, v5, v28
	v_add_f32_e32 v5, v5, v29
	s_nop 1
	v_add_f32_dpp v5, v5, v5 quad_perm:[1,0,3,2] row_mask:0xf bank_mask:0xf bound_ctrl:1
	s_nop 1
	v_add_f32_dpp v5, v5, v5 quad_perm:[2,3,0,1] row_mask:0xf bank_mask:0xf bound_ctrl:1
	s_nop 1
	v_add_f32_dpp v5, v5, v5 row_half_mirror row_mask:0xf bank_mask:0xf bound_ctrl:1
	s_nop 1
	v_add_f32_dpp v5, v5, v5 row_mirror row_mask:0xf bank_mask:0xf bound_ctrl:1
	s_nop 0
	v_readlane_b32 s6, v5, 16
	v_readlane_b32 s7, v5, 48
	v_readlane_b32 s4, v5, 0
	v_readlane_b32 s5, v5, 32
	v_mov_b32_e32 v26, s6
	v_mov_b32_e32 v27, s7
	v_pk_add_f32 v[26:27], s[4:5], v[26:27]
	s_nop 0
	v_add_f32_e32 v5, v26, v27
	v_fmamk_f32 v5, v5, 0x3a800000, v4
	v_mul_f32_e32 v26, 0x4b800000, v5
	v_cmp_gt_f32_e32 vcc, s1, v5
	s_nop 1
	v_cndmask_b32_e32 v5, v5, v26, vcc
	v_rsq_f32_e32 v5, v5
	s_nop 0
	v_mul_f32_e32 v26, 0x45800000, v5
	v_cndmask_b32_e32 v26, v5, v26, vcc
	v_pk_mul_f32 v[6:7], v[100:101], v[26:27] op_sel_hi:[1,0]
	v_pk_mul_f32 v[8:9], v[102:103], v[26:27] op_sel_hi:[1,0]
	v_pk_mul_f32 v[6:7], v[116:117], v[6:7]
	v_pk_mul_f32 v[8:9], v[118:119], v[8:9]
	global_store_dwordx4 v[2:3], v[6:9], off offset:-3072
	s_nop 0
	v_pk_mul_f32 v[12:13], v[106:107], v[26:27] op_sel_hi:[1,0]
	v_pk_mul_f32 v[10:11], v[104:105], v[26:27] op_sel_hi:[1,0]
	v_pk_mul_f32 v[8:9], v[122:123], v[12:13]
	v_pk_mul_f32 v[6:7], v[120:121], v[10:11]
	global_store_dwordx4 v[2:3], v[6:9], off offset:-2048
	s_nop 0
	v_pk_mul_f32 v[10:11], v[110:111], v[26:27] op_sel_hi:[1,0]
	v_pk_mul_f32 v[12:13], v[108:109], v[26:27] op_sel_hi:[1,0]
	v_pk_mul_f32 v[8:9], v[126:127], v[10:11]
	v_pk_mul_f32 v[6:7], v[124:125], v[12:13]
	global_store_dwordx4 v[2:3], v[6:9], off offset:-1024
	s_nop 0
	v_pk_mul_f32 v[10:11], v[114:115], v[26:27] op_sel_hi:[1,0]
	v_pk_mul_f32 v[12:13], v[112:113], v[26:27] op_sel_hi:[1,0]
	v_pk_mul_f32 v[8:9], v[130:131], v[10:11]
	v_pk_mul_f32 v[6:7], v[128:129], v[12:13]
	global_store_dwordx4 v[2:3], v[6:9], off
	v_lshl_add_u64 v[2:3], v[2:3], 0, s[2:3]
	s_cbranch_scc1 .LBB0_2632
